# attention phase: ONE static s_setprio 1 for waves 0-3 at phase entry, per-section flips deleted
# speedup vs baseline: 1.0020x; 1.0020x over previous
.LBB0_312:
	s_andn2_b64 vcc, exec, s[0:1]
	s_cbranch_vccnz .LBB0_528
	v_readlane_b32 s0, v254, 53
	v_readlane_b32 s1, v254, 54
	v_mov_b32_e32 v2, v206
	v_readlane_b32 s36, v252, 33
	v_cndmask_b32_e64 v0, 0, 1, s[0:1]
	v_lshlrev_b32_e32 v0, 2, v0
	v_lshl_add_u64 v[146:147], s[26:27], 0, v[0:1]
	v_ashrrev_i32_e32 v0, 3, v2
	v_ashrrev_i32_e32 v164, 6, v2
	v_and_b32_e32 v3, 63, v2
	v_and_b32_e32 v167, 0xffffffe0, v0
	v_mov_b32_e32 v0, 0xfffed000
	v_lshl_add_u32 v171, v164, 3, v0
	v_lshlrev_b32_e32 v0, 2, v3
	v_readlane_b32 s37, v252, 34
	v_readlane_b32 s38, v252, 35
	v_readlane_b32 s39, v252, 36
	v_readlane_b32 s40, v252, 37
	v_readlane_b32 s41, v252, 38
	v_readlane_b32 s42, v252, 39
	v_readlane_b32 s43, v252, 40
	v_readlane_b32 s44, v252, 41
	v_readlane_b32 s45, v252, 42
	v_readlane_b32 s46, v252, 43
	v_readlane_b32 s47, v252, 44
	v_readlane_b32 s48, v252, 45
	v_readlane_b32 s49, v252, 46
	v_readlane_b32 s50, v252, 47
	v_readlane_b32 s51, v252, 48
	v_lshlrev_b32_e32 v4, 11, v164
	v_lshl_add_u64 v[148:149], s[38:39], 0, v[0:1]
	v_readlane_b32 s36, v253, 33
	v_cmp_eq_u32_e64 s[72:73], 0, v2
	s_and_b64 s[0:1], s[0:1], exec
	v_lshlrev_b32_e32 v168, 5, v164
	v_ashrrev_i32_e32 v169, 7, v2
	v_or_b32_e32 v2, v4, v0
	v_lshlrev_b32_e32 v0, 4, v3
	v_readlane_b32 s46, v253, 43
	v_readlane_b32 s47, v253, 44
	v_add_u32_e32 v165, 0x18000, v4
	v_and_b32_e32 v166, 3, v164
	s_cselect_b32 s3, 8, 0
	v_and_b32_e32 v170, 32, v168
	v_cmp_eq_u32_e64 s[6:7], 0, v3
	v_or_b32_e32 v172, 0xffffffc0, v3
	v_add_u32_e32 v173, 0x18000, v2
	v_lshlrev_b16_e32 v174, 3, v164
	v_lshl_add_u64 v[150:151], s[46:47], 0, v[0:1]
	v_readlane_b32 s37, v253, 34
	v_readlane_b32 s38, v253, 35
	v_readlane_b32 s39, v253, 36
	v_readlane_b32 s40, v253, 37
	v_readlane_b32 s41, v253, 38
	v_readlane_b32 s42, v253, 39
	v_readlane_b32 s43, v253, 40
	v_readlane_b32 s44, v253, 41
	v_readlane_b32 s45, v253, 42
	v_readlane_b32 s48, v253, 45
	v_readlane_b32 s49, v253, 46
	v_readlane_b32 s50, v253, 47
	v_readlane_b32 s51, v253, 48
	v_readfirstlane_b32 s0, v206
	s_nop 3
	s_cmp_ge_u32 s0, 0x100
	s_cbranch_scc1 .Lprio_static
	s_setprio 1
